# attention units: redundant second workgroup barrier at the unit end removed (two adjacent barriers with nothing between)
# baseline (speedup 1.0000x reference)
; __device__ __forceinline__ int crow(int r,int hi){return (r&3)+8*(r>>2)+4*hi;}
; __device__ __forceinline__ unsigned cvtpk_s(float lo,float hi){f32x2_t v={lo,hi};bf16x2_t b=__builtin_convertvector(v,bf16x2_t);return __builtin_bit_cast(unsigned,b);}
; template<int THRL,int MODE,int DM,bool DRY=false> __device__ __forceinline__ void attn_unit(int b,int h,int qb,const bf16*Q,const bf16*__restrict__ K,const bf16*__restrict__ V,bf16*O,const bf16*__restrict__ Z,const float*__restrict__ XP,const int*__restrict__ TS,volatile unsigned*lw,unsigned nxt,cha ...
;     ...
;   if(hi==0)wsf[32+r32]=l_reg;asm volatile("s_waitcnt lgkmcnt(0)":::"memory");
;   float rli[16];
;   #pragma unroll
;   for(int r=0;r<16;++r)rli[r]=__builtin_amdgcn_rcpf(wsf[32+crow(r,hi)]);
;   bf16*Ow=O+(rowbase+q0+wid*QBLK)*DM+h*D;
;   { bf16*stg=(bf16*)(shm+LDS_OST)+wid*2048;
;     #pragma unroll
;     for(int r=0;r<16;++r){const int orow=crow(r,hi);
;       #pragma unroll
;       for(int d0=0;d0<2;++d0)stg[orow*64+d0*32+r32]=__float2bfloat16(o[d0][r]*rli[r]);}
;     asm volatile("s_waitcnt lgkmcnt(0)":::"memory");
;     #pragma unroll
;     for(int i=0;i<4;++i){const int row=i*8+(lane>>3),ch=lane&7; const u32x4 v=*(const u32x4*)(stg+row*64+ch*8); const u32x4 zv=zpre[i]; u32x4 ov;
;       #pragma unroll
;       for(int e=0;e<4;++e){ const float o0=__uint_as_float(v[e]<<16),o1=__uint_as_float(v[e]&0xffff0000u),z0=__uint_as_float(zv[e]<<16),z1=__uint_as_float(zv[e]&0xffff0000u);
;         ov[e]=cvtpk_s(o0*z0*__builtin_amdgcn_rcpf(1.f+__expf(-z0)),o1*z1*__builtin_amdgcn_rcpf(1.f+__expf(-z1))); }
;       if(!DRY||ov[0]==0x7fc12345u)ATTN_STORE16(Ow+(long)row*DM+ch*8,ov);} }
.LBB0_891:
	s_or_b64 exec, exec, s[8:9]
	s_waitcnt lgkmcnt(0)
	ds_read_b128 v[48:51], v98 offset:49280
	ds_read_b128 v[52:55], v98 offset:49312
	s_lshl_b32 s8, s65, 12
	s_add_i32 s8, s8, 0
	v_lshlrev_b32_e32 v64, 1, v237
	s_waitcnt lgkmcnt(0)
	v_rcp_f32_e32 v56, v48
	v_rcp_f32_e32 v57, v49
	v_lshlrev_b32_e32 v65, 9, v238
	v_add3_u32 v64, s8, v64, v65
	v_mul_f32_e32 v16, v16, v56
	v_cvt_pk_bf16_f32 v16, v16, s0
	v_rcp_f32_e32 v58, v50
	v_rcp_f32_e32 v59, v51
	v_rcp_f32_e32 v60, v52
	ds_read_b128 v[48:51], v98 offset:49344
	v_rcp_f32_e32 v61, v53
	v_rcp_f32_e32 v62, v54
	v_rcp_f32_e32 v63, v55
	ds_read_b128 v[52:55], v98 offset:49376
	ds_write_b16 v64, v16 offset:51200
	v_mul_f32_e32 v16, v32, v56
	v_cvt_pk_bf16_f32 v16, v16, s0
	ds_write_b16 v64, v16 offset:51264
	v_mul_f32_e32 v16, v17, v57
	v_cvt_pk_bf16_f32 v16, v16, s0
	ds_write_b16 v64, v16 offset:51328
	v_mul_f32_e32 v16, v33, v57
	v_cvt_pk_bf16_f32 v16, v16, s0
	ds_write_b16 v64, v16 offset:51392
	v_mul_f32_e32 v16, v18, v58
	v_cvt_pk_bf16_f32 v16, v16, s0
	ds_write_b16 v64, v16 offset:51456
	v_mul_f32_e32 v16, v34, v58
	v_cvt_pk_bf16_f32 v16, v16, s0
	ds_write_b16 v64, v16 offset:51520
	v_mul_f32_e32 v16, v19, v59
	v_cvt_pk_bf16_f32 v16, v16, s0
	ds_write_b16 v64, v16 offset:51584
	v_mul_f32_e32 v16, v35, v59
	v_cvt_pk_bf16_f32 v16, v16, s0
	ds_write_b16 v64, v16 offset:51648
	v_mul_f32_e32 v16, v20, v60
	v_cvt_pk_bf16_f32 v16, v16, s0
	ds_write_b16 v64, v16 offset:52224
	v_mul_f32_e32 v16, v36, v60
	v_cvt_pk_bf16_f32 v16, v16, s0
	ds_write_b16 v64, v16 offset:52288
	v_mul_f32_e32 v16, v21, v61
	v_cvt_pk_bf16_f32 v16, v16, s0
	ds_write_b16 v64, v16 offset:52352
	v_mul_f32_e32 v16, v37, v61
	v_cvt_pk_bf16_f32 v16, v16, s0
	ds_write_b16 v64, v16 offset:52416
	v_mul_f32_e32 v16, v22, v62
	v_cvt_pk_bf16_f32 v16, v16, s0
	ds_write_b16 v64, v16 offset:52480
	v_mul_f32_e32 v16, v38, v62
	v_cvt_pk_bf16_f32 v16, v16, s0
	s_waitcnt lgkmcnt(0)
	v_rcp_f32_e32 v48, v48
	ds_write_b16 v64, v16 offset:52544
	v_mul_f32_e32 v16, v23, v63
	v_cvt_pk_bf16_f32 v16, v16, s0
	ds_write_b16 v64, v16 offset:52608
	v_mul_f32_e32 v16, v39, v63
	v_cvt_pk_bf16_f32 v16, v16, s0
	v_rcp_f32_e32 v49, v49
	ds_write_b16 v64, v16 offset:52672
	v_mul_f32_e32 v16, v24, v48
	v_cvt_pk_bf16_f32 v16, v16, s0
	ds_write_b16 v64, v16 offset:53248
	v_mul_f32_e32 v16, v40, v48
	v_cvt_pk_bf16_f32 v16, v16, s0
	v_rcp_f32_e32 v50, v50
	ds_write_b16 v64, v16 offset:53312
	v_mul_f32_e32 v16, v25, v49
	v_cvt_pk_bf16_f32 v16, v16, s0
	ds_write_b16 v64, v16 offset:53376
	v_mul_f32_e32 v16, v41, v49
	v_cvt_pk_bf16_f32 v16, v16, s0
	v_rcp_f32_e32 v51, v51
	ds_write_b16 v64, v16 offset:53440
	v_mul_f32_e32 v16, v26, v50
	v_cvt_pk_bf16_f32 v16, v16, s0
	ds_write_b16 v64, v16 offset:53504
	v_mul_f32_e32 v16, v42, v50
	v_cvt_pk_bf16_f32 v16, v16, s0
	v_rcp_f32_e32 v52, v52
	ds_write_b16 v64, v16 offset:53568
	v_mul_f32_e32 v16, v27, v51
	v_cvt_pk_bf16_f32 v16, v16, s0
	ds_write_b16 v64, v16 offset:53632
	v_mul_f32_e32 v16, v43, v51
	v_cvt_pk_bf16_f32 v16, v16, s0
	v_rcp_f32_e32 v53, v53
	ds_write_b16 v64, v16 offset:53696
	v_mul_f32_e32 v16, v28, v52
	v_cvt_pk_bf16_f32 v16, v16, s0
	ds_write_b16 v64, v16 offset:54272
	v_mul_f32_e32 v16, v44, v52
	v_cvt_pk_bf16_f32 v16, v16, s0
	v_rcp_f32_e32 v54, v54
	ds_write_b16 v64, v16 offset:54336
	v_mul_f32_e32 v16, v29, v53
	v_cvt_pk_bf16_f32 v16, v16, s0
	ds_write_b16 v64, v16 offset:54400
	v_mul_f32_e32 v16, v45, v53
	v_cvt_pk_bf16_f32 v16, v16, s0
	v_rcp_f32_e32 v55, v55
	ds_write_b16 v64, v16 offset:54464
	v_mul_f32_e32 v16, v30, v54
	v_cvt_pk_bf16_f32 v16, v16, s0
	ds_write_b16 v64, v16 offset:54528
	v_mul_f32_e32 v16, v46, v54
	v_cvt_pk_bf16_f32 v16, v16, s0
	ds_write_b16 v64, v16 offset:54592
	v_mul_f32_e32 v16, v31, v55
	v_cvt_pk_bf16_f32 v16, v16, s0
	ds_write_b16 v64, v16 offset:54656
	v_mul_f32_e32 v16, v47, v55
	v_cvt_pk_bf16_f32 v16, v16, s0
	ds_write_b16 v64, v16 offset:54720
	v_lshlrev_b32_e32 v16, 7, v99
	s_waitcnt vmcnt(0)
	v_lshlrev_b32_e32 v20, 16, v92
	v_add3_u32 v30, s8, v222, v16
	v_and_b32_e32 v23, 0xffff0000, v92
	v_mul_f32_e32 v16, 0xbfb8aa3b, v20
	v_exp_f32_e32 v21, v16
	v_mul_f32_e32 v16, 0xbfb8aa3b, v23
	v_exp_f32_e32 v22, v16
	s_waitcnt lgkmcnt(0)
	ds_read_b128 v[16:19], v30 offset:51200
	v_add_f32_e32 v21, 1.0, v21
	v_rcp_f32_e32 v26, v21
	v_add_f32_e32 v21, 1.0, v22
	v_rcp_f32_e32 v27, v21
	s_waitcnt lgkmcnt(0)
	v_and_b32_e32 v21, 0xffff0000, v16
	v_lshlrev_b32_e32 v22, 16, v16
	v_pk_mul_f32 v[20:21], v[22:23], v[20:21]
	v_lshlrev_b32_e32 v22, 16, v93
	v_pk_mul_f32 v[20:21], v[26:27], v[20:21]
	v_and_b32_e32 v27, 0xffff0000, v93
	v_mul_f32_e32 v16, 0xbfb8aa3b, v22
	v_exp_f32_e32 v16, v16
	v_mul_f32_e32 v23, 0xbfb8aa3b, v27
	v_exp_f32_e32 v23, v23
	v_lshlrev_b32_e32 v26, 16, v17
	v_add_f32_e32 v16, 1.0, v16
	v_rcp_f32_e32 v28, v16
	v_add_f32_e32 v16, 1.0, v23
	v_and_b32_e32 v23, 0xffff0000, v17
	v_rcp_f32_e32 v29, v16
	v_pk_mul_f32 v[16:17], v[26:27], v[22:23]
	v_lshlrev_b32_e32 v22, 16, v94
	v_cvt_pk_bf16_f32 v20, v20, v21
	v_and_b32_e32 v27, 0xffff0000, v94
	v_mul_f32_e32 v21, 0xbfb8aa3b, v22
	v_exp_f32_e32 v23, v21
	v_mul_f32_e32 v21, 0xbfb8aa3b, v27
	v_exp_f32_e32 v26, v21
	v_pk_mul_f32 v[16:17], v[28:29], v[16:17]
	v_and_b32_e32 v29, 0xffff0000, v95
	v_cvt_pk_bf16_f32 v21, v16, v17
	v_add_f32_e32 v16, 1.0, v23
	v_add_f32_e32 v17, 1.0, v26
	v_rcp_f32_e32 v16, v16
	v_rcp_f32_e32 v17, v17
	v_and_b32_e32 v23, 0xffff0000, v18
	v_lshlrev_b32_e32 v26, 16, v18
	v_pk_mul_f32 v[22:23], v[26:27], v[22:23]
	v_lshlrev_b32_e32 v26, 16, v95
	v_pk_mul_f32 v[16:17], v[16:17], v[22:23]
	v_mul_f32_e32 v18, 0xbfb8aa3b, v26
	v_mul_f32_e32 v22, 0xbfb8aa3b, v29
	v_exp_f32_e32 v18, v18
	v_exp_f32_e32 v23, v22
	v_cvt_pk_bf16_f32 v22, v16, v17
	v_and_b32_e32 v27, 0xffff0000, v19
	v_add_f32_e32 v16, 1.0, v18
	v_add_f32_e32 v17, 1.0, v23
	v_rcp_f32_e32 v16, v16
	v_rcp_f32_e32 v17, v17
	v_lshlrev_b32_e32 v28, 16, v19
	v_pk_mul_f32 v[18:19], v[28:29], v[26:27]
	v_lshl_add_u64 v[24:25], s[58:59], 0, v[222:223]
	v_pk_mul_f32 v[16:17], v[16:17], v[18:19]
	v_mov_b32_e32 v97, v223
	v_cvt_pk_bf16_f32 v23, v16, v17
	v_lshl_add_u64 v[16:17], v[24:25], 0, v[96:97]
	global_store_dwordx4 v[16:17], v[20:23], off
	v_and_b32_e32 v25, 0xffff0000, v88
	s_cmp_lg_u32 s3, -1
	v_lshlrev_b32_e32 v22, 16, v88
	v_mul_f32_e32 v18, 0xbfb8aa3b, v22
	v_exp_f32_e32 v23, v18
	v_mul_f32_e32 v18, 0xbfb8aa3b, v25
	v_exp_f32_e32 v24, v18
	ds_read_b128 v[18:21], v30 offset:52224
	v_add_f32_e32 v23, 1.0, v23
	v_rcp_f32_e32 v26, v23
	v_add_f32_e32 v23, 1.0, v24
	v_rcp_f32_e32 v27, v23
	s_waitcnt lgkmcnt(0)
; __device__ __forceinline__ unsigned cvtpk_s(float lo,float hi){f32x2_t v={lo,hi};bf16x2_t b=__builtin_convertvector(v,bf16x2_t);return __builtin_bit_cast(unsigned,b);}
; #define BAR_LDS() asm volatile("s_waitcnt lgkmcnt(0)\n\ts_barrier" ::: "memory")
; template<int THRL,int MODE,int DM,bool DRY=false> __device__ __forceinline__ void attn_unit(int b,int h,int qb,const bf16*Q,const bf16*__restrict__ K,const bf16*__restrict__ V,bf16*O,const bf16*__restrict__ Z,const float*__restrict__ XP,const int*__restrict__ TS,volatile unsigned*lw,unsigned nxt,cha ...
;     ...
;     for(int i=0;i<4;++i){const int row=i*8+(lane>>3),ch=lane&7; const u32x4 v=*(const u32x4*)(stg+row*64+ch*8); const u32x4 zv=zpre[i]; u32x4 ov;
;       #pragma unroll
;       for(int e=0;e<4;++e){ const float o0=__uint_as_float(v[e]<<16),o1=__uint_as_float(v[e]&0xffff0000u),z0=__uint_as_float(zv[e]<<16),z1=__uint_as_float(zv[e]&0xffff0000u);
;         ov[e]=cvtpk_s(o0*z0*__builtin_amdgcn_rcpf(1.f+__expf(-z0)),o1*z1*__builtin_amdgcn_rcpf(1.f+__expf(-z1))); }
;       if(!DRY||ov[0]==0x7fc12345u)ATTN_STORE16(Ow+(long)row*DM+ch*8,ov);} }
;   asm volatile("s_waitcnt lgkmcnt(0)\n\ts_barrier":::"memory");
; template <bool DRY> __device__ __forceinline__ void moba_phase(const Args& A, char* lds, int vcu, int G) {
;     ...
;         BAR_LDS();
;         u = __builtin_amdgcn_readfirstlane((int)lw[0]);
	v_and_b32_e32 v23, 0xffff0000, v18
	v_lshlrev_b32_e32 v24, 16, v18
	v_pk_mul_f32 v[22:23], v[24:25], v[22:23]
	v_lshlrev_b32_e32 v24, 16, v89
	v_pk_mul_f32 v[22:23], v[26:27], v[22:23]
	v_and_b32_e32 v27, 0xffff0000, v89
	v_mul_f32_e32 v18, 0xbfb8aa3b, v24
	v_exp_f32_e32 v25, v18
	v_mul_f32_e32 v18, 0xbfb8aa3b, v27
	v_exp_f32_e32 v26, v18
	v_cvt_pk_bf16_f32 v18, v22, v23
	v_add_f32_e32 v22, 1.0, v25
	v_rcp_f32_e32 v22, v22
	v_add_f32_e32 v23, 1.0, v26
	v_rcp_f32_e32 v23, v23
	v_and_b32_e32 v25, 0xffff0000, v19
	v_lshlrev_b32_e32 v26, 16, v19
	v_pk_mul_f32 v[24:25], v[26:27], v[24:25]
	v_and_b32_e32 v27, 0xffff0000, v90
	v_pk_mul_f32 v[22:23], v[22:23], v[24:25]
	v_lshlrev_b32_e32 v24, 16, v90
	v_mul_f32_e32 v19, 0xbfb8aa3b, v24
	v_exp_f32_e32 v25, v19
	v_mul_f32_e32 v19, 0xbfb8aa3b, v27
	v_exp_f32_e32 v26, v19
	v_cvt_pk_bf16_f32 v19, v22, v23
	v_add_f32_e32 v22, 1.0, v25
	v_rcp_f32_e32 v22, v22
	v_add_f32_e32 v23, 1.0, v26
	v_rcp_f32_e32 v23, v23
	v_and_b32_e32 v25, 0xffff0000, v20
	v_lshlrev_b32_e32 v26, 16, v20
	v_pk_mul_f32 v[24:25], v[26:27], v[24:25]
	v_and_b32_e32 v27, 0xffff0000, v91
	v_pk_mul_f32 v[22:23], v[22:23], v[24:25]
	v_lshlrev_b32_e32 v24, 16, v91
	v_mul_f32_e32 v20, 0xbfb8aa3b, v24
	v_exp_f32_e32 v25, v20
	v_mul_f32_e32 v20, 0xbfb8aa3b, v27
	v_exp_f32_e32 v26, v20
	v_cvt_pk_bf16_f32 v20, v22, v23
	v_add_f32_e32 v22, 1.0, v25
	v_rcp_f32_e32 v22, v22
	v_add_f32_e32 v23, 1.0, v26
	v_rcp_f32_e32 v23, v23
	v_and_b32_e32 v25, 0xffff0000, v21
	v_lshlrev_b32_e32 v26, 16, v21
	v_pk_mul_f32 v[24:25], v[26:27], v[24:25]
	s_cselect_b32 s8, s3, 0
	v_pk_mul_f32 v[22:23], v[22:23], v[24:25]
	v_and_b32_e32 v25, 0xffff0000, v84
	v_cvt_pk_bf16_f32 v21, v22, v23
	v_add_co_u32_e32 v22, vcc, s1, v16
	s_cselect_b32 s9, s27, 0
	s_nop 0
	v_addc_co_u32_e32 v23, vcc, 0, v17, vcc
	global_store_dwordx4 v[22:23], v[18:21], off
	v_lshlrev_b32_e32 v22, 16, v84
	s_nop 0
	v_mul_f32_e32 v18, 0xbfb8aa3b, v22
	v_exp_f32_e32 v23, v18
	v_mul_f32_e32 v18, 0xbfb8aa3b, v25
	v_exp_f32_e32 v24, v18
	ds_read_b128 v[18:21], v30 offset:53248
	v_add_f32_e32 v23, 1.0, v23
	v_rcp_f32_e32 v26, v23
	v_add_f32_e32 v23, 1.0, v24
	v_rcp_f32_e32 v27, v23
	s_waitcnt lgkmcnt(0)
	v_and_b32_e32 v23, 0xffff0000, v18
	v_lshlrev_b32_e32 v24, 16, v18
	v_pk_mul_f32 v[22:23], v[24:25], v[22:23]
	v_lshlrev_b32_e32 v24, 16, v85
	v_pk_mul_f32 v[22:23], v[26:27], v[22:23]
	v_and_b32_e32 v27, 0xffff0000, v85
	v_mul_f32_e32 v18, 0xbfb8aa3b, v24
	v_exp_f32_e32 v25, v18
	v_mul_f32_e32 v18, 0xbfb8aa3b, v27
	v_exp_f32_e32 v26, v18
	v_cvt_pk_bf16_f32 v18, v22, v23
	v_add_f32_e32 v22, 1.0, v25
	v_rcp_f32_e32 v22, v22
	v_add_f32_e32 v23, 1.0, v26
	v_rcp_f32_e32 v23, v23
	v_and_b32_e32 v25, 0xffff0000, v19
	v_lshlrev_b32_e32 v26, 16, v19
	v_pk_mul_f32 v[24:25], v[26:27], v[24:25]
	v_and_b32_e32 v27, 0xffff0000, v86
	v_pk_mul_f32 v[22:23], v[22:23], v[24:25]
	v_lshlrev_b32_e32 v24, 16, v86
	v_mul_f32_e32 v19, 0xbfb8aa3b, v24
	v_exp_f32_e32 v25, v19
	v_mul_f32_e32 v19, 0xbfb8aa3b, v27
	v_exp_f32_e32 v26, v19
	v_cvt_pk_bf16_f32 v19, v22, v23
	v_add_f32_e32 v22, 1.0, v25
	v_rcp_f32_e32 v22, v22
	v_add_f32_e32 v23, 1.0, v26
	v_rcp_f32_e32 v23, v23
	v_and_b32_e32 v25, 0xffff0000, v20
	v_lshlrev_b32_e32 v26, 16, v20
	v_pk_mul_f32 v[24:25], v[26:27], v[24:25]
	v_and_b32_e32 v27, 0xffff0000, v87
	v_pk_mul_f32 v[22:23], v[22:23], v[24:25]
	v_lshlrev_b32_e32 v24, 16, v87
	v_mul_f32_e32 v20, 0xbfb8aa3b, v24
	v_exp_f32_e32 v25, v20
	v_mul_f32_e32 v20, 0xbfb8aa3b, v27
	v_exp_f32_e32 v26, v20
	v_cvt_pk_bf16_f32 v20, v22, v23
	v_add_f32_e32 v22, 1.0, v25
	v_rcp_f32_e32 v22, v22
	v_add_f32_e32 v23, 1.0, v26
	v_rcp_f32_e32 v23, v23
	v_and_b32_e32 v25, 0xffff0000, v21
	v_lshlrev_b32_e32 v26, 16, v21
	v_pk_mul_f32 v[24:25], v[26:27], v[24:25]
	s_nop 0
	v_pk_mul_f32 v[22:23], v[22:23], v[24:25]
	v_and_b32_e32 v25, 0xffff0000, v80
	v_cvt_pk_bf16_f32 v21, v22, v23
	v_add_co_u32_e32 v22, vcc, s89, v16
	s_nop 1
	v_addc_co_u32_e32 v23, vcc, 0, v17, vcc
	global_store_dwordx4 v[22:23], v[18:21], off
	v_lshlrev_b32_e32 v22, 16, v80
	v_add_co_u32_e32 v16, vcc, s90, v16
	v_mul_f32_e32 v18, 0xbfb8aa3b, v22
	v_exp_f32_e32 v23, v18
	v_mul_f32_e32 v18, 0xbfb8aa3b, v25
	v_exp_f32_e32 v24, v18
	ds_read_b128 v[18:21], v30 offset:54272
	v_add_f32_e32 v23, 1.0, v23
	v_rcp_f32_e32 v26, v23
	v_add_f32_e32 v23, 1.0, v24
	v_rcp_f32_e32 v27, v23
	s_waitcnt lgkmcnt(0)
	v_and_b32_e32 v23, 0xffff0000, v18
	v_lshlrev_b32_e32 v24, 16, v18
	v_pk_mul_f32 v[22:23], v[24:25], v[22:23]
	v_lshlrev_b32_e32 v24, 16, v81
	v_pk_mul_f32 v[22:23], v[26:27], v[22:23]
	v_and_b32_e32 v27, 0xffff0000, v81
	v_mul_f32_e32 v18, 0xbfb8aa3b, v24
	v_exp_f32_e32 v25, v18
	v_mul_f32_e32 v18, 0xbfb8aa3b, v27
	v_exp_f32_e32 v26, v18
	v_cvt_pk_bf16_f32 v18, v22, v23
	v_add_f32_e32 v22, 1.0, v25
	v_rcp_f32_e32 v22, v22
	v_add_f32_e32 v23, 1.0, v26
	v_rcp_f32_e32 v23, v23
	v_and_b32_e32 v25, 0xffff0000, v19
	v_lshlrev_b32_e32 v26, 16, v19
	v_pk_mul_f32 v[24:25], v[26:27], v[24:25]
	v_and_b32_e32 v27, 0xffff0000, v82
	v_pk_mul_f32 v[22:23], v[22:23], v[24:25]
	v_lshlrev_b32_e32 v24, 16, v82
	v_mul_f32_e32 v19, 0xbfb8aa3b, v24
	v_exp_f32_e32 v25, v19
	v_mul_f32_e32 v19, 0xbfb8aa3b, v27
	v_exp_f32_e32 v26, v19
	v_cvt_pk_bf16_f32 v19, v22, v23
	v_add_f32_e32 v22, 1.0, v25
	v_rcp_f32_e32 v22, v22
	v_add_f32_e32 v23, 1.0, v26
	v_rcp_f32_e32 v23, v23
	v_and_b32_e32 v25, 0xffff0000, v20
	v_lshlrev_b32_e32 v26, 16, v20
	v_pk_mul_f32 v[24:25], v[26:27], v[24:25]
	v_and_b32_e32 v27, 0xffff0000, v83
	v_pk_mul_f32 v[22:23], v[22:23], v[24:25]
	v_lshlrev_b32_e32 v24, 16, v83
	v_mul_f32_e32 v20, 0xbfb8aa3b, v24
	v_exp_f32_e32 v25, v20
	v_mul_f32_e32 v20, 0xbfb8aa3b, v27
	v_exp_f32_e32 v26, v20
	v_cvt_pk_bf16_f32 v20, v22, v23
	v_add_f32_e32 v22, 1.0, v25
	v_rcp_f32_e32 v22, v22
	v_add_f32_e32 v23, 1.0, v26
	v_rcp_f32_e32 v23, v23
	v_and_b32_e32 v25, 0xffff0000, v21
	v_lshlrev_b32_e32 v26, 16, v21
	v_pk_mul_f32 v[24:25], v[26:27], v[24:25]
	v_addc_co_u32_e32 v17, vcc, 0, v17, vcc
	v_pk_mul_f32 v[22:23], v[22:23], v[24:25]
	s_nop 0
	v_cvt_pk_bf16_f32 v21, v22, v23
	global_store_dwordx4 v[16:17], v[18:21], off
	s_waitcnt lgkmcnt(0)
	s_barrier
	v_mov_b32_e32 v16, s8
	v_mov_b32_e32 v17, s9
	ds_read_b32 v16, v16
	s_waitcnt lgkmcnt(0)
	v_readfirstlane_b32 s10, v16
	s_cmpk_lt_i32 s10, 0x400
	s_cbranch_scc0 .LBB0_984

; __device__ __forceinline__ int crow(int r,int hi){return (r&3)+8*(r>>2)+4*hi;}
; __device__ __forceinline__ unsigned cvtpk_s(float lo,float hi){f32x2_t v={lo,hi};bf16x2_t b=__builtin_convertvector(v,bf16x2_t);return __builtin_bit_cast(unsigned,b);}
; template<int THRL,int MODE,int DM,bool DRY=false> __device__ __forceinline__ void attn_unit(int b,int h,int qb,const bf16*Q,const bf16*__restrict__ K,const bf16*__restrict__ V,bf16*O,const bf16*__restrict__ Z,const float*__restrict__ XP,const int*__restrict__ TS,volatile unsigned*lw,unsigned nxt,cha ...
;     ...
;   if(hi==0)wsf[32+r32]=l_reg;asm volatile("s_waitcnt lgkmcnt(0)":::"memory");
;   float rli[16];
;   #pragma unroll
;   for(int r=0;r<16;++r)rli[r]=__builtin_amdgcn_rcpf(wsf[32+crow(r,hi)]);
;   bf16*Ow=O+(rowbase+q0+wid*QBLK)*DM+h*D;
;   { bf16*stg=(bf16*)(shm+LDS_OST)+wid*2048;
;     #pragma unroll
;     for(int r=0;r<16;++r){const int orow=crow(r,hi);
;       #pragma unroll
;       for(int d0=0;d0<2;++d0)stg[orow*64+d0*32+r32]=__float2bfloat16(o[d0][r]*rli[r]);}
;     asm volatile("s_waitcnt lgkmcnt(0)":::"memory");
;     #pragma unroll
;     for(int i=0;i<4;++i){const int row=i*8+(lane>>3),ch=lane&7; const u32x4 v=*(const u32x4*)(stg+row*64+ch*8); const u32x4 zv=zpre[i]; u32x4 ov;
;       #pragma unroll
;       for(int e=0;e<4;++e){ const float o0=__uint_as_float(v[e]<<16),o1=__uint_as_float(v[e]&0xffff0000u),z0=__uint_as_float(zv[e]<<16),z1=__uint_as_float(zv[e]&0xffff0000u);
;         ov[e]=cvtpk_s(o0*z0*__builtin_amdgcn_rcpf(1.f+__expf(-z0)),o1*z1*__builtin_amdgcn_rcpf(1.f+__expf(-z1))); }
;       if(!DRY||ov[0]==0x7fc12345u)ATTN_STORE16(Ow+(long)row*DM+ch*8,ov);} }
.LBB0_1435:
	s_or_b64 exec, exec, s[8:9]
	s_waitcnt lgkmcnt(0)
	ds_read_b128 v[32:35], v83 offset:49280
	ds_read_b128 v[36:39], v83 offset:49312
	s_lshl_b32 s8, s81, 12
	s_add_i32 s8, s8, 0
	v_lshlrev_b32_e32 v48, 1, v208
	s_waitcnt lgkmcnt(0)
	v_rcp_f32_e32 v40, v32
	v_rcp_f32_e32 v41, v33
	v_lshlrev_b32_e32 v49, 9, v209
	v_add3_u32 v48, s8, v48, v49
	v_mul_f32_e32 v0, v0, v40
	v_cvt_pk_bf16_f32 v0, v0, s0
	v_rcp_f32_e32 v42, v34
	v_rcp_f32_e32 v43, v35
	v_rcp_f32_e32 v44, v36
	ds_read_b128 v[32:35], v83 offset:49344
	v_rcp_f32_e32 v45, v37
	v_rcp_f32_e32 v46, v38
	v_rcp_f32_e32 v47, v39
	ds_read_b128 v[36:39], v83 offset:49376
	ds_write_b16 v48, v0 offset:51264
	v_mul_f32_e32 v0, v17, v41
	v_cvt_pk_bf16_f32 v0, v0, s0
	ds_write_b16 v48, v0 offset:51328
	v_mul_f32_e32 v0, v1, v41
	v_cvt_pk_bf16_f32 v0, v0, s0
	ds_write_b16 v48, v0 offset:51392
	v_mul_f32_e32 v0, v18, v42
	v_cvt_pk_bf16_f32 v0, v0, s0
	ds_write_b16 v48, v0 offset:51456
	v_mul_f32_e32 v0, v2, v42
	v_cvt_pk_bf16_f32 v0, v0, s0
	ds_write_b16 v48, v0 offset:51520
	v_mul_f32_e32 v0, v19, v43
	v_cvt_pk_bf16_f32 v0, v0, s0
	ds_write_b16 v48, v0 offset:51584
	v_mul_f32_e32 v0, v3, v43
	v_cvt_pk_bf16_f32 v0, v0, s0
	ds_write_b16 v48, v0 offset:51648
	v_mul_f32_e32 v0, v20, v44
	v_cvt_pk_bf16_f32 v0, v0, s0
	ds_write_b16 v48, v0 offset:52224
	v_mul_f32_e32 v0, v4, v44
	v_cvt_pk_bf16_f32 v0, v0, s0
	ds_write_b16 v48, v0 offset:52288
	v_mul_f32_e32 v0, v21, v45
	v_cvt_pk_bf16_f32 v0, v0, s0
	ds_write_b16 v48, v0 offset:52352
	v_mul_f32_e32 v0, v5, v45
	v_cvt_pk_bf16_f32 v0, v0, s0
	ds_write_b16 v48, v0 offset:52416
	v_mul_f32_e32 v0, v22, v46
	v_cvt_pk_bf16_f32 v0, v0, s0
	ds_write_b16 v48, v0 offset:52480
	v_mul_f32_e32 v0, v6, v46
	v_cvt_pk_bf16_f32 v0, v0, s0
	s_waitcnt lgkmcnt(0)
	v_rcp_f32_e32 v32, v32
	ds_write_b16 v48, v0 offset:52544
	v_mul_f32_e32 v0, v23, v47
	v_cvt_pk_bf16_f32 v0, v0, s0
	ds_write_b16 v48, v0 offset:52608
	v_mul_f32_e32 v0, v7, v47
	v_cvt_pk_bf16_f32 v0, v0, s0
	v_rcp_f32_e32 v33, v33
	ds_write_b16 v48, v0 offset:52672
	v_mul_f32_e32 v0, v24, v32
	v_cvt_pk_bf16_f32 v0, v0, s0
	ds_write_b16 v48, v0 offset:53248
	v_mul_f32_e32 v0, v8, v32
	v_cvt_pk_bf16_f32 v0, v0, s0
	v_rcp_f32_e32 v34, v34
	ds_write_b16 v48, v0 offset:53312
	v_mul_f32_e32 v0, v25, v33
	v_cvt_pk_bf16_f32 v0, v0, s0
	ds_write_b16 v48, v0 offset:53376
	v_mul_f32_e32 v0, v9, v33
	v_cvt_pk_bf16_f32 v0, v0, s0
	v_rcp_f32_e32 v35, v35
	ds_write_b16 v48, v0 offset:53440
	v_mul_f32_e32 v0, v26, v34
	v_cvt_pk_bf16_f32 v0, v0, s0
	ds_write_b16 v48, v0 offset:53504
	v_mul_f32_e32 v0, v10, v34
	v_cvt_pk_bf16_f32 v0, v0, s0
	v_rcp_f32_e32 v36, v36
	ds_write_b16 v48, v0 offset:53568
	v_mul_f32_e32 v0, v27, v35
	v_cvt_pk_bf16_f32 v0, v0, s0
	ds_write_b16 v48, v0 offset:53632
	v_mul_f32_e32 v0, v11, v35
	v_cvt_pk_bf16_f32 v0, v0, s0
	v_rcp_f32_e32 v37, v37
	ds_write_b16 v48, v0 offset:53696
	v_mul_f32_e32 v0, v28, v36
	v_cvt_pk_bf16_f32 v0, v0, s0
	ds_write_b16 v48, v0 offset:54272
	v_mul_f32_e32 v0, v12, v36
	v_cvt_pk_bf16_f32 v0, v0, s0
	v_rcp_f32_e32 v38, v38
	ds_write_b16 v48, v0 offset:54336
	v_mul_f32_e32 v0, v29, v37
	v_cvt_pk_bf16_f32 v0, v0, s0
	ds_write_b16 v48, v0 offset:54400
	v_mul_f32_e32 v0, v13, v37
	v_cvt_pk_bf16_f32 v0, v0, s0
	v_rcp_f32_e32 v39, v39
	ds_write_b16 v48, v0 offset:54464
	v_mul_f32_e32 v0, v30, v38
	v_cvt_pk_bf16_f32 v0, v0, s0
	ds_write_b16 v48, v0 offset:54528
	v_mul_f32_e32 v0, v14, v38
	v_cvt_pk_bf16_f32 v0, v0, s0
	ds_write_b16 v48, v0 offset:54592
	v_mul_f32_e32 v0, v31, v39
	v_cvt_pk_bf16_f32 v0, v0, s0
	ds_write_b16 v48, v0 offset:54656
	v_mul_f32_e32 v0, v15, v39
	v_cvt_pk_bf16_f32 v0, v0, s0
	ds_write_b16 v48, v0 offset:54720
	v_lshlrev_b32_e32 v0, 7, v84
	s_waitcnt vmcnt(0)
	v_lshlrev_b32_e32 v4, 16, v76
	v_mul_f32_e32 v16, v16, v40
	v_add3_u32 v14, s8, v192, v0
	v_and_b32_e32 v7, 0xffff0000, v76
	v_mul_f32_e32 v0, 0xbfb8aa3b, v4
	v_cvt_pk_bf16_f32 v16, v16, s0
	v_exp_f32_e32 v5, v0
	v_mul_f32_e32 v0, 0xbfb8aa3b, v7
	ds_write_b16 v48, v16 offset:51200
	v_exp_f32_e32 v6, v0
	s_waitcnt lgkmcnt(0)
	ds_read_b128 v[0:3], v14 offset:51200
	v_add_f32_e32 v5, 1.0, v5
	v_rcp_f32_e32 v10, v5
	v_add_f32_e32 v5, 1.0, v6
	v_rcp_f32_e32 v11, v5
	s_waitcnt lgkmcnt(0)
	v_and_b32_e32 v5, 0xffff0000, v0
	v_lshlrev_b32_e32 v6, 16, v0
	v_pk_mul_f32 v[4:5], v[6:7], v[4:5]
	v_lshlrev_b32_e32 v6, 16, v77
	v_pk_mul_f32 v[4:5], v[10:11], v[4:5]
	v_and_b32_e32 v11, 0xffff0000, v77
	v_mul_f32_e32 v0, 0xbfb8aa3b, v6
	v_exp_f32_e32 v0, v0
	v_mul_f32_e32 v7, 0xbfb8aa3b, v11
	v_exp_f32_e32 v7, v7
	v_lshlrev_b32_e32 v10, 16, v1
	v_add_f32_e32 v0, 1.0, v0
	v_rcp_f32_e32 v12, v0
	v_add_f32_e32 v0, 1.0, v7
	v_and_b32_e32 v7, 0xffff0000, v1
	v_rcp_f32_e32 v13, v0
	v_pk_mul_f32 v[0:1], v[10:11], v[6:7]
	v_lshlrev_b32_e32 v6, 16, v78
	v_cvt_pk_bf16_f32 v4, v4, v5
	v_and_b32_e32 v11, 0xffff0000, v78
	v_mul_f32_e32 v5, 0xbfb8aa3b, v6
	v_exp_f32_e32 v7, v5
	v_mul_f32_e32 v5, 0xbfb8aa3b, v11
	v_exp_f32_e32 v10, v5
	v_pk_mul_f32 v[0:1], v[12:13], v[0:1]
	v_and_b32_e32 v13, 0xffff0000, v79
	v_cvt_pk_bf16_f32 v5, v0, v1
	v_add_f32_e32 v0, 1.0, v7
	v_add_f32_e32 v1, 1.0, v10
	v_rcp_f32_e32 v0, v0
	v_rcp_f32_e32 v1, v1
	v_and_b32_e32 v7, 0xffff0000, v2
	v_lshlrev_b32_e32 v10, 16, v2
	v_pk_mul_f32 v[6:7], v[10:11], v[6:7]
	v_lshlrev_b32_e32 v10, 16, v79
	v_pk_mul_f32 v[0:1], v[0:1], v[6:7]
	v_mul_f32_e32 v2, 0xbfb8aa3b, v10
	v_mul_f32_e32 v6, 0xbfb8aa3b, v13
	v_exp_f32_e32 v2, v2
	v_exp_f32_e32 v7, v6
	v_cvt_pk_bf16_f32 v6, v0, v1
	v_and_b32_e32 v11, 0xffff0000, v3
	v_add_f32_e32 v0, 1.0, v2
	v_add_f32_e32 v1, 1.0, v7
	v_rcp_f32_e32 v0, v0
	v_rcp_f32_e32 v1, v1
	v_lshlrev_b32_e32 v12, 16, v3
	v_pk_mul_f32 v[2:3], v[12:13], v[10:11]
	v_lshl_add_u64 v[8:9], s[50:51], 0, v[192:193]
	v_pk_mul_f32 v[0:1], v[0:1], v[2:3]
	v_mov_b32_e32 v81, v193
	v_cvt_pk_bf16_f32 v7, v0, v1
	v_lshl_add_u64 v[0:1], v[8:9], 0, v[80:81]
	global_store_dwordx4 v[0:1], v[4:7], off
	v_and_b32_e32 v9, 0xffff0000, v72
	s_cmp_lg_u32 s3, -1
	v_lshlrev_b32_e32 v6, 16, v72
	v_mul_f32_e32 v2, 0xbfb8aa3b, v6
	v_exp_f32_e32 v7, v2
	v_mul_f32_e32 v2, 0xbfb8aa3b, v9
	v_exp_f32_e32 v8, v2
	ds_read_b128 v[2:5], v14 offset:52224
	v_add_f32_e32 v7, 1.0, v7
	v_rcp_f32_e32 v10, v7
	v_add_f32_e32 v7, 1.0, v8
	v_rcp_f32_e32 v11, v7
	s_waitcnt lgkmcnt(0)
; __device__ __forceinline__ unsigned cvtpk_s(float lo,float hi){f32x2_t v={lo,hi};bf16x2_t b=__builtin_convertvector(v,bf16x2_t);return __builtin_bit_cast(unsigned,b);}
; #define BAR_LDS() asm volatile("s_waitcnt lgkmcnt(0)\n\ts_barrier" ::: "memory")
; template<int THRL,int MODE,int DM,bool DRY=false> __device__ __forceinline__ void attn_unit(int b,int h,int qb,const bf16*Q,const bf16*__restrict__ K,const bf16*__restrict__ V,bf16*O,const bf16*__restrict__ Z,const float*__restrict__ XP,const int*__restrict__ TS,volatile unsigned*lw,unsigned nxt,cha ...
;     ...
;     for(int i=0;i<4;++i){const int row=i*8+(lane>>3),ch=lane&7; const u32x4 v=*(const u32x4*)(stg+row*64+ch*8); const u32x4 zv=zpre[i]; u32x4 ov;
;       #pragma unroll
;       for(int e=0;e<4;++e){ const float o0=__uint_as_float(v[e]<<16),o1=__uint_as_float(v[e]&0xffff0000u),z0=__uint_as_float(zv[e]<<16),z1=__uint_as_float(zv[e]&0xffff0000u);
;         ov[e]=cvtpk_s(o0*z0*__builtin_amdgcn_rcpf(1.f+__expf(-z0)),o1*z1*__builtin_amdgcn_rcpf(1.f+__expf(-z1))); }
;       if(!DRY||ov[0]==0x7fc12345u)ATTN_STORE16(Ow+(long)row*DM+ch*8,ov);} }
;   asm volatile("s_waitcnt lgkmcnt(0)\n\ts_barrier":::"memory");
; template <bool DRY> __device__ __forceinline__ void fox_phase(const Args& A, char* lds, int vcu, int G) {
;     ...
;         BAR_LDS();
;         u = __builtin_amdgcn_readfirstlane((int)lw[0]);
	v_and_b32_e32 v7, 0xffff0000, v2
	v_lshlrev_b32_e32 v8, 16, v2
	v_pk_mul_f32 v[6:7], v[8:9], v[6:7]
	v_lshlrev_b32_e32 v8, 16, v73
	v_pk_mul_f32 v[6:7], v[10:11], v[6:7]
	v_and_b32_e32 v11, 0xffff0000, v73
	v_mul_f32_e32 v2, 0xbfb8aa3b, v8
	v_exp_f32_e32 v9, v2
	v_mul_f32_e32 v2, 0xbfb8aa3b, v11
	v_exp_f32_e32 v10, v2
	v_cvt_pk_bf16_f32 v2, v6, v7
	v_add_f32_e32 v6, 1.0, v9
	v_rcp_f32_e32 v6, v6
	v_add_f32_e32 v7, 1.0, v10
	v_rcp_f32_e32 v7, v7
	v_and_b32_e32 v9, 0xffff0000, v3
	v_lshlrev_b32_e32 v10, 16, v3
	v_pk_mul_f32 v[8:9], v[10:11], v[8:9]
	v_and_b32_e32 v11, 0xffff0000, v74
	v_pk_mul_f32 v[6:7], v[6:7], v[8:9]
	v_lshlrev_b32_e32 v8, 16, v74
	v_mul_f32_e32 v3, 0xbfb8aa3b, v8
	v_exp_f32_e32 v9, v3
	v_mul_f32_e32 v3, 0xbfb8aa3b, v11
	v_exp_f32_e32 v10, v3
	v_cvt_pk_bf16_f32 v3, v6, v7
	v_add_f32_e32 v6, 1.0, v9
	v_rcp_f32_e32 v6, v6
	v_add_f32_e32 v7, 1.0, v10
	v_rcp_f32_e32 v7, v7
	v_and_b32_e32 v9, 0xffff0000, v4
	v_lshlrev_b32_e32 v10, 16, v4
	v_pk_mul_f32 v[8:9], v[10:11], v[8:9]
	v_and_b32_e32 v11, 0xffff0000, v75
	v_pk_mul_f32 v[6:7], v[6:7], v[8:9]
	v_lshlrev_b32_e32 v8, 16, v75
	v_mul_f32_e32 v4, 0xbfb8aa3b, v8
	v_exp_f32_e32 v9, v4
	v_mul_f32_e32 v4, 0xbfb8aa3b, v11
	v_exp_f32_e32 v10, v4
	v_cvt_pk_bf16_f32 v4, v6, v7
	v_add_f32_e32 v6, 1.0, v9
	v_rcp_f32_e32 v6, v6
	v_add_f32_e32 v7, 1.0, v10
	v_rcp_f32_e32 v7, v7
	v_and_b32_e32 v9, 0xffff0000, v5
	v_lshlrev_b32_e32 v10, 16, v5
	v_pk_mul_f32 v[8:9], v[10:11], v[8:9]
	s_cselect_b32 s8, s3, 0
	v_pk_mul_f32 v[6:7], v[6:7], v[8:9]
	v_and_b32_e32 v9, 0xffff0000, v68
	v_cvt_pk_bf16_f32 v5, v6, v7
	v_add_co_u32_e32 v6, vcc, s78, v0
	s_cselect_b32 s9, s19, 0
	s_nop 0
	v_addc_co_u32_e32 v7, vcc, 0, v1, vcc
	global_store_dwordx4 v[6:7], v[2:5], off
	v_lshlrev_b32_e32 v6, 16, v68
	s_nop 0
	v_mul_f32_e32 v2, 0xbfb8aa3b, v6
	v_exp_f32_e32 v7, v2
	v_mul_f32_e32 v2, 0xbfb8aa3b, v9
	v_exp_f32_e32 v8, v2
	ds_read_b128 v[2:5], v14 offset:53248
	v_add_f32_e32 v7, 1.0, v7
	v_rcp_f32_e32 v10, v7
	v_add_f32_e32 v7, 1.0, v8
	v_rcp_f32_e32 v11, v7
	s_waitcnt lgkmcnt(0)
	v_and_b32_e32 v7, 0xffff0000, v2
	v_lshlrev_b32_e32 v8, 16, v2
	v_pk_mul_f32 v[6:7], v[8:9], v[6:7]
	v_lshlrev_b32_e32 v8, 16, v69
	v_pk_mul_f32 v[6:7], v[10:11], v[6:7]
	v_and_b32_e32 v11, 0xffff0000, v69
	v_mul_f32_e32 v2, 0xbfb8aa3b, v8
	v_exp_f32_e32 v9, v2
	v_mul_f32_e32 v2, 0xbfb8aa3b, v11
	v_exp_f32_e32 v10, v2
	v_cvt_pk_bf16_f32 v2, v6, v7
	v_add_f32_e32 v6, 1.0, v9
	v_rcp_f32_e32 v6, v6
	v_add_f32_e32 v7, 1.0, v10
	v_rcp_f32_e32 v7, v7
	v_and_b32_e32 v9, 0xffff0000, v3
	v_lshlrev_b32_e32 v10, 16, v3
	v_pk_mul_f32 v[8:9], v[10:11], v[8:9]
	v_and_b32_e32 v11, 0xffff0000, v70
	v_pk_mul_f32 v[6:7], v[6:7], v[8:9]
	v_lshlrev_b32_e32 v8, 16, v70
	v_mul_f32_e32 v3, 0xbfb8aa3b, v8
	v_exp_f32_e32 v9, v3
	v_mul_f32_e32 v3, 0xbfb8aa3b, v11
	v_exp_f32_e32 v10, v3
	v_cvt_pk_bf16_f32 v3, v6, v7
	v_add_f32_e32 v6, 1.0, v9
	v_rcp_f32_e32 v6, v6
	v_add_f32_e32 v7, 1.0, v10
	v_rcp_f32_e32 v7, v7
	v_and_b32_e32 v9, 0xffff0000, v4
	v_lshlrev_b32_e32 v10, 16, v4
	v_pk_mul_f32 v[8:9], v[10:11], v[8:9]
	v_and_b32_e32 v11, 0xffff0000, v71
	v_pk_mul_f32 v[6:7], v[6:7], v[8:9]
	v_lshlrev_b32_e32 v8, 16, v71
	v_mul_f32_e32 v4, 0xbfb8aa3b, v8
	v_exp_f32_e32 v9, v4
	v_mul_f32_e32 v4, 0xbfb8aa3b, v11
	v_exp_f32_e32 v10, v4
	v_cvt_pk_bf16_f32 v4, v6, v7
	v_add_f32_e32 v6, 1.0, v9
	v_rcp_f32_e32 v6, v6
	v_add_f32_e32 v7, 1.0, v10
	v_rcp_f32_e32 v7, v7
	v_and_b32_e32 v9, 0xffff0000, v5
	v_lshlrev_b32_e32 v10, 16, v5
	v_pk_mul_f32 v[8:9], v[10:11], v[8:9]
	s_nop 0
	v_pk_mul_f32 v[6:7], v[6:7], v[8:9]
	v_and_b32_e32 v9, 0xffff0000, v64
	v_cvt_pk_bf16_f32 v5, v6, v7
	v_add_co_u32_e32 v6, vcc, s79, v0
	s_nop 1
	v_addc_co_u32_e32 v7, vcc, 0, v1, vcc
	global_store_dwordx4 v[6:7], v[2:5], off
	v_lshlrev_b32_e32 v6, 16, v64
	v_add_co_u32_e32 v0, vcc, s80, v0
	v_mul_f32_e32 v2, 0xbfb8aa3b, v6
	v_exp_f32_e32 v7, v2
	v_mul_f32_e32 v2, 0xbfb8aa3b, v9
	v_exp_f32_e32 v8, v2
	ds_read_b128 v[2:5], v14 offset:54272
	v_add_f32_e32 v7, 1.0, v7
	v_rcp_f32_e32 v10, v7
	v_add_f32_e32 v7, 1.0, v8
	v_rcp_f32_e32 v11, v7
	s_waitcnt lgkmcnt(0)
	v_and_b32_e32 v7, 0xffff0000, v2
	v_lshlrev_b32_e32 v8, 16, v2
	v_pk_mul_f32 v[6:7], v[8:9], v[6:7]
	v_lshlrev_b32_e32 v8, 16, v65
	v_pk_mul_f32 v[6:7], v[10:11], v[6:7]
	v_and_b32_e32 v11, 0xffff0000, v65
	v_mul_f32_e32 v2, 0xbfb8aa3b, v8
	v_exp_f32_e32 v9, v2
	v_mul_f32_e32 v2, 0xbfb8aa3b, v11
	v_exp_f32_e32 v10, v2
	v_cvt_pk_bf16_f32 v2, v6, v7
	v_add_f32_e32 v6, 1.0, v9
	v_rcp_f32_e32 v6, v6
	v_add_f32_e32 v7, 1.0, v10
	v_rcp_f32_e32 v7, v7
	v_and_b32_e32 v9, 0xffff0000, v3
	v_lshlrev_b32_e32 v10, 16, v3
	v_pk_mul_f32 v[8:9], v[10:11], v[8:9]
	v_and_b32_e32 v11, 0xffff0000, v66
	v_pk_mul_f32 v[6:7], v[6:7], v[8:9]
	v_lshlrev_b32_e32 v8, 16, v66
	v_mul_f32_e32 v3, 0xbfb8aa3b, v8
	v_exp_f32_e32 v9, v3
	v_mul_f32_e32 v3, 0xbfb8aa3b, v11
	v_exp_f32_e32 v10, v3
	v_cvt_pk_bf16_f32 v3, v6, v7
	v_add_f32_e32 v6, 1.0, v9
	v_rcp_f32_e32 v6, v6
	v_add_f32_e32 v7, 1.0, v10
	v_rcp_f32_e32 v7, v7
	v_and_b32_e32 v9, 0xffff0000, v4
	v_lshlrev_b32_e32 v10, 16, v4
	v_pk_mul_f32 v[8:9], v[10:11], v[8:9]
	v_and_b32_e32 v11, 0xffff0000, v67
	v_pk_mul_f32 v[6:7], v[6:7], v[8:9]
	v_lshlrev_b32_e32 v8, 16, v67
	v_mul_f32_e32 v4, 0xbfb8aa3b, v8
	v_exp_f32_e32 v9, v4
	v_mul_f32_e32 v4, 0xbfb8aa3b, v11
	v_exp_f32_e32 v10, v4
	v_cvt_pk_bf16_f32 v4, v6, v7
	v_add_f32_e32 v6, 1.0, v9
	v_rcp_f32_e32 v6, v6
	v_add_f32_e32 v7, 1.0, v10
	v_rcp_f32_e32 v7, v7
	v_and_b32_e32 v9, 0xffff0000, v5
	v_lshlrev_b32_e32 v10, 16, v5
	v_pk_mul_f32 v[8:9], v[10:11], v[8:9]
	v_addc_co_u32_e32 v1, vcc, 0, v1, vcc
	v_pk_mul_f32 v[6:7], v[6:7], v[8:9]
	s_nop 0
	v_cvt_pk_bf16_f32 v5, v6, v7
	global_store_dwordx4 v[0:1], v[2:5], off
	s_waitcnt lgkmcnt(0)
	s_barrier
	v_mov_b32_e32 v0, s8
	v_mov_b32_e32 v1, s9
	ds_read_b32 v0, v0
	s_waitcnt lgkmcnt(0)
	v_readfirstlane_b32 s10, v0
	s_cmpk_lt_i32 s10, 0x600
	s_cbranch_scc0 .LBB0_1531
